# counted vmcnt waits at first use instead of a full wait for the first x / h2+ple load batch of the P4 and P5 tile epilogues
# speedup vs baseline: 1.0045x; 1.0045x over previous
; __device__ __forceinline__ unsigned cvt_pk_bf16(float lo, float hi) { const f32x2_t v = {lo, hi}; const bf16x2_t b = __builtin_convertvector(v, bf16x2_t); return __builtin_bit_cast(unsigned, b); }
;     __device__ __forceinline__ void operator()(f32x4 (&acc)[2][2][4][2], const Unit& u, int wr, int wc, int fr, int fq) const {
;     ...
;             for (int m = 0; m < 4; ++m) { const float* xrow = xb + (size_t)EPI_ROWS(ai, m) * DM + c0;
; #pragma unroll
;                 for (int bj = 0; bj < 2; ++bj) { xv[m][bj][0] = __builtin_nontemporal_load((const f32x4*)(xrow + 32 * bj)); xv[m][bj][1] = __builtin_nontemporal_load((const f32x4*)(xrow + 32 * bj + 4)); } }
;             asm volatile("" ::: "memory");
; #pragma unroll
;             for (int m = 0; m < 4; ++m) {
;                 const int r = EPI_ROWS(ai, m);
;                 float ss = 0.f;
; #pragma unroll
;                 for (int bj = 0; bj < 2; ++bj) {
;                     const f32x4 h0 = acc[ai][bj][m][0] + xv[m][bj][0], h1 = acc[ai][bj][m][1] + xv[m][bj][1];
;                     ss += (h0[0] * h0[0] + h0[1] * h0[1]) + (h0[2] * h0[2] + h0[3] * h0[3]) + (h1[0] * h1[0] + h1[1] * h1[1]) + (h1[2] * h1[2] + h1[3] * h1[3]);
;                     u32x4 w; w.x = cvt_pk_bf16(h0[0], h0[1]); w.y = cvt_pk_bf16(h0[2], h0[3]); w.z = cvt_pk_bf16(h1[0], h1[1]); w.w = cvt_pk_bf16(h1[2], h1[3]);
;                     *(u32x4*)(HP + (size_t)r * LDHP + c0 + 32 * bj) = w;
;                 }
;                 ss += __shfl_xor(ss, 16); ss += __shfl_xor(ss, 32);
;                 if (fq == 0) SS[(size_t)r * 16 + u.pn * 4 + wc] = ss;
.LBB0_902:
	s_cmpk_lt_i32 s74, 0x80
	v_lshl_or_b32 v204, s72, 8, v217
	s_cselect_b32 s0, s65, s34
	s_cselect_b32 s2, s64, s31
	v_lshl_add_u32 v208, s74, 8, v1
	v_mov_b32_e32 v130, s2
	v_mov_b32_e32 v131, s0
	v_ashrrev_i32_e32 v205, 31, v204
	v_ashrrev_i32_e32 v209, 31, v208
	v_lshl_add_u64 v[206:207], v[204:205], 2, v[130:131]
	v_lshlrev_b64 v[130:131], 12, v[208:209]
	v_lshl_add_u64 v[130:131], v[206:207], 0, v[130:131]
	global_load_dwordx4 v[224:227], v[130:131], off offset:16 nt
	global_load_dwordx4 v[228:231], v[130:131], off nt
	global_load_dwordx4 v[178:181], v[130:131], off offset:144 nt
	global_load_dwordx4 v[182:185], v[130:131], off offset:128 nt
	v_or_b32_e32 v214, 16, v208
	v_ashrrev_i32_e32 v215, 31, v214
	v_lshlrev_b64 v[130:131], 12, v[214:215]
	v_or_b32_e32 v212, 32, v208
	v_lshl_add_u64 v[130:131], v[206:207], 0, v[130:131]
	v_ashrrev_i32_e32 v213, 31, v212
	global_load_dwordx4 v[170:173], v[130:131], off offset:16 nt
	global_load_dwordx4 v[174:177], v[130:131], off nt
	global_load_dwordx4 v[162:165], v[130:131], off offset:144 nt
	global_load_dwordx4 v[166:169], v[130:131], off offset:128 nt
	v_lshlrev_b64 v[130:131], 12, v[212:213]
	v_or_b32_e32 v210, 48, v208
	v_lshl_add_u64 v[130:131], v[206:207], 0, v[130:131]
	v_ashrrev_i32_e32 v211, 31, v210
	global_load_dwordx4 v[154:157], v[130:131], off offset:16 nt
	global_load_dwordx4 v[158:161], v[130:131], off nt
	global_load_dwordx4 v[138:141], v[130:131], off offset:144 nt
	global_load_dwordx4 v[146:149], v[130:131], off offset:128 nt
	v_lshlrev_b64 v[130:131], 12, v[210:211]
	v_lshl_add_u64 v[134:135], v[206:207], 0, v[130:131]
	global_load_dwordx4 v[142:145], v[134:135], off offset:16 nt
	global_load_dwordx4 v[150:153], v[134:135], off nt
	global_load_dwordx4 v[130:133], v[134:135], off offset:144 nt
	s_nop 0
	global_load_dwordx4 v[134:137], v[134:135], off offset:128 nt
	v_and_b32_e32 v223, 64, v221
	v_xor_b32_e32 v222, 16, v221
	v_add_u32_e32 v223, 64, v223
	v_cmp_lt_i32_e32 vcc, v222, v223
	v_xor_b32_e32 v232, 32, v221
	s_lshl_b32 s66, s72, 2
	v_cndmask_b32_e32 v222, v221, v222, vcc
	v_lshlrev_b32_e32 v222, 2, v222
	v_cmp_lt_i32_e32 vcc, v232, v223
	s_ashr_i32 s67, s66, 31
	s_waitcnt vmcnt(15)
	v_pk_add_f32 v[226:227], v[124:125], v[226:227]
	s_waitcnt vmcnt(14)
	v_pk_add_f32 v[128:129], v[128:129], v[230:231]
	v_pk_add_f32 v[126:127], v[126:127], v[228:229]
	v_pk_add_f32 v[124:125], v[122:123], v[224:225]
	v_mul_f32_e32 v122, v127, v127
	v_mul_f32_e32 v123, v129, v129
	v_fmac_f32_e32 v122, v126, v126
	v_fmac_f32_e32 v123, v128, v128
	v_add_f32_e32 v122, v122, v123
	v_mul_f32_e32 v123, v125, v125
	v_fmac_f32_e32 v123, v124, v124
	v_add_f32_e32 v122, v122, v123
	v_mul_f32_e32 v123, v227, v227
	v_fmac_f32_e32 v123, v226, v226
	v_add_f32_e32 v224, v123, v122
	v_cvt_pk_bf16_f32 v122, v126, v127
	v_mov_b64_e32 v[126:127], s[82:83]
	v_mad_i64_i32 v[126:127], s[2:3], v208, s54, v[126:127]
	v_cvt_pk_bf16_f32 v123, v128, v129
	v_cvt_pk_bf16_f32 v124, v124, v125
	v_cvt_pk_bf16_f32 v125, v226, v227
	v_lshl_add_u64 v[126:127], v[204:205], 1, v[126:127]
	s_waitcnt vmcnt(12)
	v_pk_add_f32 v[120:121], v[120:121], v[184:185]
	v_pk_add_f32 v[118:119], v[118:119], v[182:183]
	global_store_dwordx4 v[126:127], v[122:125], off
	v_cndmask_b32_e32 v223, v221, v232, vcc
	v_lshlrev_b32_e32 v223, 2, v223
	v_pk_add_f32 v[122:123], v[116:117], v[180:181]
	v_pk_add_f32 v[116:117], v[114:115], v[178:179]
	v_mul_f32_e32 v114, v119, v119
	v_mul_f32_e32 v115, v121, v121
	v_fmac_f32_e32 v114, v118, v118
	v_fmac_f32_e32 v115, v120, v120
	v_add_f32_e32 v114, v114, v115
	v_mul_f32_e32 v115, v117, v117
	v_fmac_f32_e32 v115, v116, v116
	v_add_f32_e32 v114, v114, v115
	v_mul_f32_e32 v115, v123, v123
	v_fmac_f32_e32 v115, v122, v122
	v_add_f32_e32 v114, v115, v114
	v_add_f32_e32 v124, v224, v114
	v_cvt_pk_bf16_f32 v114, v118, v119
	v_cvt_pk_bf16_f32 v115, v120, v121
	v_cvt_pk_bf16_f32 v116, v116, v117
	v_cvt_pk_bf16_f32 v117, v122, v123
	global_store_dwordx4 v[126:127], v[114:117], off offset:64
	ds_bpermute_b32 v114, v222, v124
	s_waitcnt lgkmcnt(0)
	v_add_f32_e32 v114, v124, v114
	ds_bpermute_b32 v115, v223, v114
	s_and_saveexec_b64 s[18:19], s[40:41]
	s_cbranch_execz .LBB0_904
	v_lshlrev_b64 v[116:117], 6, v[208:209]
	v_lshl_add_u64 v[116:117], s[8:9], 0, v[116:117]
	v_lshl_add_u64 v[116:117], s[66:67], 2, v[116:117]
	s_lshl_b32 s0, s30, 2
	v_lshl_add_u64 v[116:117], v[116:117], 0, s[0:1]
	s_waitcnt lgkmcnt(0)
	v_add_f32_e32 v114, v114, v115
	global_store_dword v[116:117], v114, off
; __device__ __forceinline__ unsigned cvt_pk_bf16(float lo, float hi) { const f32x2_t v = {lo, hi}; const bf16x2_t b = __builtin_convertvector(v, bf16x2_t); return __builtin_bit_cast(unsigned, b); }
;     __device__ __forceinline__ void operator()(f32x4 (&acc)[2][2][4][2], const Unit& u, int wr, int wc, int fr, int fq) const {
;     ...
;             for (int m = 0; m < 4; ++m) {
;                 const int r = EPI_ROWS(ai, m);
;                 float ss = 0.f;
; #pragma unroll
;                 for (int bj = 0; bj < 2; ++bj) {
;                     const f32x4 h0 = acc[ai][bj][m][0] + xv[m][bj][0], h1 = acc[ai][bj][m][1] + xv[m][bj][1];
;                     ss += (h0[0] * h0[0] + h0[1] * h0[1]) + (h0[2] * h0[2] + h0[3] * h0[3]) + (h1[0] * h1[0] + h1[1] * h1[1]) + (h1[2] * h1[2] + h1[3] * h1[3]);
;                     u32x4 w; w.x = cvt_pk_bf16(h0[0], h0[1]); w.y = cvt_pk_bf16(h0[2], h0[3]); w.z = cvt_pk_bf16(h1[0], h1[1]); w.w = cvt_pk_bf16(h1[2], h1[3]);
;                     *(u32x4*)(HP + (size_t)r * LDHP + c0 + 32 * bj) = w;
;                 }
;                 ss += __shfl_xor(ss, 16); ss += __shfl_xor(ss, 32);
;                 if (fq == 0) SS[(size_t)r * 16 + u.pn * 4 + wc] = ss;
.LBB0_904:
	s_or_b64 exec, exec, s[18:19]
	s_waitcnt vmcnt(12)
	v_pk_add_f32 v[112:113], v[112:113], v[176:177]
	v_pk_add_f32 v[110:111], v[110:111], v[174:175]
	s_waitcnt lgkmcnt(0)
	v_pk_add_f32 v[114:115], v[108:109], v[172:173]
	v_pk_add_f32 v[108:109], v[106:107], v[170:171]
	v_mul_f32_e32 v106, v111, v111
	v_mul_f32_e32 v107, v113, v113
	v_fmac_f32_e32 v106, v110, v110
	v_fmac_f32_e32 v107, v112, v112
	v_add_f32_e32 v106, v106, v107
	v_mul_f32_e32 v107, v109, v109
	v_fmac_f32_e32 v107, v108, v108
	v_add_f32_e32 v106, v106, v107
	v_mul_f32_e32 v107, v115, v115
	s_waitcnt vmcnt(10)
	v_pk_add_f32 v[104:105], v[104:105], v[168:169]
	v_pk_add_f32 v[102:103], v[102:103], v[166:167]
	v_fmac_f32_e32 v107, v114, v114
	v_cvt_pk_bf16_f32 v108, v108, v109
	v_cvt_pk_bf16_f32 v109, v114, v115
	v_pk_add_f32 v[114:115], v[98:99], v[162:163]
	v_mul_f32_e32 v98, v103, v103
	v_mul_f32_e32 v99, v105, v105
	v_fmac_f32_e32 v98, v102, v102
	v_fmac_f32_e32 v99, v104, v104
	v_add_f32_e32 v98, v98, v99
	v_mul_f32_e32 v99, v115, v115
	v_add_f32_e32 v116, v107, v106
	v_cvt_pk_bf16_f32 v107, v112, v113
	v_pk_add_f32 v[112:113], v[100:101], v[164:165]
	v_fmac_f32_e32 v99, v114, v114
	v_add_f32_e32 v98, v98, v99
	v_mul_f32_e32 v99, v113, v113
	v_fmac_f32_e32 v99, v112, v112
	v_add_f32_e32 v98, v99, v98
	v_add_f32_e32 v101, v116, v98
	ds_bpermute_b32 v116, v222, v101
	v_cvt_pk_bf16_f32 v106, v110, v111
	v_mov_b64_e32 v[110:111], s[82:83]
	v_mad_i64_i32 v[98:99], s[2:3], v214, s54, v[110:111]
	v_lshl_add_u64 v[110:111], v[204:205], 1, v[98:99]
	s_waitcnt lgkmcnt(0)
	v_add_f32_e32 v98, v101, v116
	ds_bpermute_b32 v99, v223, v98
	v_cvt_pk_bf16_f32 v100, v102, v103
	v_cvt_pk_bf16_f32 v101, v104, v105
	v_cvt_pk_bf16_f32 v102, v114, v115
	v_cvt_pk_bf16_f32 v103, v112, v113
	global_store_dwordx4 v[110:111], v[106:109], off
	global_store_dwordx4 v[110:111], v[100:103], off offset:64
	s_and_saveexec_b64 s[18:19], s[40:41]
	s_cbranch_execz .LBB0_906
	v_lshlrev_b64 v[100:101], 6, v[214:215]
	v_lshl_add_u64 v[100:101], s[8:9], 0, v[100:101]
	v_lshl_add_u64 v[100:101], s[66:67], 2, v[100:101]
	s_lshl_b32 s0, s30, 2
	v_lshl_add_u64 v[100:101], v[100:101], 0, s[0:1]
	s_waitcnt lgkmcnt(0)
	v_add_f32_e32 v98, v98, v99
	global_store_dword v[100:101], v98, off
.LBB0_906:
	s_or_b64 exec, exec, s[18:19]
	s_waitcnt vmcnt(10)
	v_pk_add_f32 v[96:97], v[96:97], v[160:161]
	v_pk_add_f32 v[94:95], v[94:95], v[158:159]
	s_waitcnt lgkmcnt(0)
	v_pk_add_f32 v[98:99], v[92:93], v[156:157]
	v_pk_add_f32 v[92:93], v[90:91], v[154:155]
	v_mul_f32_e32 v90, v95, v95
	v_mul_f32_e32 v91, v97, v97
	v_fmac_f32_e32 v90, v94, v94
	v_fmac_f32_e32 v91, v96, v96
	v_add_f32_e32 v90, v90, v91
	v_mul_f32_e32 v91, v93, v93
	v_fmac_f32_e32 v91, v92, v92
	v_add_f32_e32 v90, v90, v91
	v_mul_f32_e32 v91, v99, v99
	s_waitcnt vmcnt(8)
	v_pk_add_f32 v[88:89], v[88:89], v[148:149]
	v_pk_add_f32 v[86:87], v[86:87], v[146:147]
	v_fmac_f32_e32 v91, v98, v98
	v_cvt_pk_bf16_f32 v92, v92, v93
	v_cvt_pk_bf16_f32 v93, v98, v99
	v_pk_add_f32 v[98:99], v[82:83], v[138:139]
	v_mul_f32_e32 v82, v87, v87
	v_mul_f32_e32 v83, v89, v89
	v_fmac_f32_e32 v82, v86, v86
	v_fmac_f32_e32 v83, v88, v88
	v_add_f32_e32 v82, v82, v83
	v_mul_f32_e32 v83, v99, v99
	v_add_f32_e32 v100, v91, v90
	v_cvt_pk_bf16_f32 v91, v96, v97
	v_pk_add_f32 v[96:97], v[84:85], v[140:141]
	v_fmac_f32_e32 v83, v98, v98
	v_add_f32_e32 v82, v82, v83
	v_mul_f32_e32 v83, v97, v97
	v_fmac_f32_e32 v83, v96, v96
	v_add_f32_e32 v82, v83, v82
	v_add_f32_e32 v85, v100, v82
	ds_bpermute_b32 v100, v222, v85
	v_cvt_pk_bf16_f32 v90, v94, v95
	v_mov_b64_e32 v[94:95], s[82:83]
	v_mad_i64_i32 v[82:83], s[2:3], v212, s54, v[94:95]
	v_lshl_add_u64 v[94:95], v[204:205], 1, v[82:83]
	s_waitcnt lgkmcnt(0)
	v_add_f32_e32 v82, v85, v100
	ds_bpermute_b32 v83, v223, v82
	v_cvt_pk_bf16_f32 v84, v86, v87
	v_cvt_pk_bf16_f32 v85, v88, v89
	v_cvt_pk_bf16_f32 v86, v98, v99
	v_cvt_pk_bf16_f32 v87, v96, v97
	global_store_dwordx4 v[94:95], v[90:93], off
	global_store_dwordx4 v[94:95], v[84:87], off offset:64
	s_and_saveexec_b64 s[18:19], s[40:41]
	s_cbranch_execz .LBB0_908
	v_lshlrev_b64 v[84:85], 6, v[212:213]
	v_lshl_add_u64 v[84:85], s[8:9], 0, v[84:85]
	v_lshl_add_u64 v[84:85], s[66:67], 2, v[84:85]
	s_lshl_b32 s0, s30, 2
	v_lshl_add_u64 v[84:85], v[84:85], 0, s[0:1]
	s_waitcnt lgkmcnt(0)
	v_add_f32_e32 v82, v82, v83
	global_store_dword v[84:85], v82, off
.LBB0_908:
	s_or_b64 exec, exec, s[18:19]
	s_waitcnt vmcnt(8)
	v_pk_add_f32 v[80:81], v[80:81], v[152:153]
	v_pk_add_f32 v[78:79], v[78:79], v[150:151]
	s_waitcnt lgkmcnt(0)
	v_pk_add_f32 v[82:83], v[76:77], v[144:145]
	v_pk_add_f32 v[76:77], v[74:75], v[142:143]
	v_mul_f32_e32 v74, v79, v79
	v_mul_f32_e32 v75, v81, v81
	v_fmac_f32_e32 v74, v78, v78
	v_fmac_f32_e32 v75, v80, v80
	v_add_f32_e32 v74, v74, v75
	v_mul_f32_e32 v75, v77, v77
	v_fmac_f32_e32 v75, v76, v76
	v_add_f32_e32 v74, v74, v75
	v_mul_f32_e32 v75, v83, v83
	s_waitcnt vmcnt(6)
	v_pk_add_f32 v[72:73], v[72:73], v[136:137]
	v_pk_add_f32 v[70:71], v[70:71], v[134:135]
	v_fmac_f32_e32 v75, v82, v82
	v_cvt_pk_bf16_f32 v76, v76, v77
	v_cvt_pk_bf16_f32 v77, v82, v83
	v_pk_add_f32 v[82:83], v[66:67], v[130:131]
	v_mul_f32_e32 v66, v71, v71
	v_mul_f32_e32 v67, v73, v73
	v_fmac_f32_e32 v66, v70, v70
	v_fmac_f32_e32 v67, v72, v72
	v_add_f32_e32 v66, v66, v67
	v_mul_f32_e32 v67, v83, v83
	v_add_f32_e32 v84, v75, v74
	v_cvt_pk_bf16_f32 v75, v80, v81
	v_pk_add_f32 v[80:81], v[68:69], v[132:133]
	v_fmac_f32_e32 v67, v82, v82
	v_add_f32_e32 v66, v66, v67
	v_mul_f32_e32 v67, v81, v81
	v_fmac_f32_e32 v67, v80, v80
	v_add_f32_e32 v66, v67, v66
	v_add_f32_e32 v69, v84, v66
	ds_bpermute_b32 v84, v222, v69
	v_cvt_pk_bf16_f32 v74, v78, v79
	v_mov_b64_e32 v[78:79], s[82:83]
	v_mad_i64_i32 v[66:67], s[2:3], v210, s54, v[78:79]
	v_lshl_add_u64 v[78:79], v[204:205], 1, v[66:67]
	s_waitcnt lgkmcnt(0)
	v_add_f32_e32 v66, v69, v84
	ds_bpermute_b32 v67, v223, v66
	v_cvt_pk_bf16_f32 v68, v70, v71
	v_cvt_pk_bf16_f32 v69, v72, v73
	v_cvt_pk_bf16_f32 v70, v82, v83
	v_cvt_pk_bf16_f32 v71, v80, v81
	global_store_dwordx4 v[78:79], v[74:77], off
	global_store_dwordx4 v[78:79], v[68:71], off offset:64
	s_and_saveexec_b64 s[18:19], s[40:41]
	s_cbranch_execz .LBB0_910
	v_lshlrev_b64 v[68:69], 6, v[210:211]
	v_lshl_add_u64 v[68:69], s[8:9], 0, v[68:69]
	v_lshl_add_u64 v[68:69], s[66:67], 2, v[68:69]
	s_lshl_b32 s0, s30, 2
	v_lshl_add_u64 v[68:69], v[68:69], 0, s[0:1]
	s_waitcnt lgkmcnt(0)
	v_add_f32_e32 v66, v66, v67
	global_store_dword v[68:69], v66, off

; __device__ __forceinline__ float bf_lo(unsigned w) { return __uint_as_float(w << 16); }
; __device__ __forceinline__ float bf_hi(unsigned w) { return __uint_as_float(w & 0xffff0000u); }
; __device__ __forceinline__ float sigmoidf_(float x) { return fast_rcp(1.f + fast_exp2(-LOG2E * x)); }
;     __device__ __forceinline__ void operator()(f32x4 (&acc)[2][2][4][2], const Unit& u, int wr, int wc, int fr, int fq) const {
;     ...
;             for (int m = 0; m < 4; ++m) { const int r = EPI_ROWS(ai, m);
; #pragma unroll
;                 for (int bj = 0; bj < 2; ++bj) { pw[m][bj] = *(const u32x4*)(PLE + (size_t)r * DM + c0 + 32 * bj); hw[m][bj] = *(const u32x4*)(HP + (size_t)r * LDHP + c0 + 32 * bj); }
;                 if (rs) rstd[m] = rs[u.ti * 256 + ai * HALF + wr * 64 + m * 16 + fr];
;                 else { const f32x4* sp = (const f32x4*)(SS + (size_t)r * 16); const f32x4 s0 = sp[0], s1 = sp[1], s2 = sp[2], s3 = sp[3];
;                     const float st = ((s0[0] + s0[1]) + (s0[2] + s0[3])) + ((s1[0] + s1[1]) + (s1[2] + s1[3])) + ((s2[0] + s2[1]) + (s2[2] + s2[3])) + ((s3[0] + s3[1]) + (s3[2] + s3[3]));
;                     rstd[m] = rsqrtf(st * (1.f / DM) + EPS); } }
;             asm volatile("" ::: "memory");
; #pragma unroll
;             for (int m = 0; m < 4; ++m) {
;                 float* orow = out + (size_t)EPI_ROWS(ai, m) * DM + c0;
; #pragma unroll
;                 for (int bj = 0; bj < 2; ++bj) {
;                     const f32x4 a0 = acc[ai][bj][m][0], a1 = acc[ai][bj][m][1];
;                     const u32x4 p = pw[m][bj], hh = hw[m][bj];
;                     f32x4 y0, y1;
;                     y0[0] = bf_lo(hh[0]) + sigmoidf_(rstd[m] * a0[0]) * bf_lo(p[0]); y0[1] = bf_hi(hh[0]) + sigmoidf_(rstd[m] * a0[1]) * bf_hi(p[0]);
;                     y0[2] = bf_lo(hh[1]) + sigmoidf_(rstd[m] * a0[2]) * bf_lo(p[1]); y0[3] = bf_hi(hh[1]) + sigmoidf_(rstd[m] * a0[3]) * bf_hi(p[1]);
;                     y1[0] = bf_lo(hh[2]) + sigmoidf_(rstd[m] * a1[0]) * bf_lo(p[2]); y1[1] = bf_hi(hh[2]) + sigmoidf_(rstd[m] * a1[1]) * bf_hi(p[2]);
;                     y1[2] = bf_lo(hh[3]) + sigmoidf_(rstd[m] * a1[2]) * bf_lo(p[3]); y1[3] = bf_hi(hh[3]) + sigmoidf_(rstd[m] * a1[3]) * bf_hi(p[3]);
;                     __builtin_nontemporal_store(y0, (f32x4*)(orow + 32 * bj)); __builtin_nontemporal_store(y1, (f32x4*)(orow + 32 * bj + 4));
.LBB0_1012:
	s_waitcnt lgkmcnt(0)
	v_mul_f32_e32 v238, v124, v237
	v_mul_f32_e32 v239, v125, v237
	v_mul_f32_e32 v238, 0xbfb8aa3b, v238
	v_mul_f32_e32 v239, 0xbfb8aa3b, v239
	v_exp_f32_e32 v238, v238
	v_exp_f32_e32 v239, v239
	s_waitcnt vmcnt(15)
	v_lshlrev_b32_e32 v242, 16, v184
	v_and_b32_e32 v243, 0xffff0000, v184
	v_mul_f32_e32 v184, v126, v237
	v_add_f32_e32 v238, 1.0, v238
	v_add_f32_e32 v239, 1.0, v239
	s_waitcnt vmcnt(13)
	v_lshlrev_b32_e32 v240, 16, v188
	v_and_b32_e32 v241, 0xffff0000, v188
	v_mul_f32_e32 v184, 0xbfb8aa3b, v184
	v_mul_f32_e32 v188, v127, v237
	v_rcp_f32_e32 v238, v238
	v_rcp_f32_e32 v239, v239
	v_exp_f32_e32 v184, v184
	v_mul_f32_e32 v188, 0xbfb8aa3b, v188
	v_exp_f32_e32 v188, v188
	v_pk_fma_f32 v[238:239], v[238:239], v[242:243], v[240:241]
	v_add_f32_e32 v184, 1.0, v184
	v_mul_f32_e32 v242, v120, v237
	v_mul_f32_e32 v243, v121, v237
	v_rcp_f32_e32 v240, v184
	v_add_f32_e32 v184, 1.0, v188
	v_mul_f32_e32 v242, 0xbfb8aa3b, v242
	v_mul_f32_e32 v243, 0xbfb8aa3b, v243
	v_rcp_f32_e32 v241, v184
	v_exp_f32_e32 v242, v242
	v_exp_f32_e32 v243, v243
	v_lshlrev_b32_e32 v188, 16, v189
	v_and_b32_e32 v189, 0xffff0000, v189
	v_lshlrev_b32_e32 v184, 16, v185
	v_and_b32_e32 v185, 0xffff0000, v185
	v_pk_fma_f32 v[240:241], v[240:241], v[184:185], v[188:189]
	v_add_f32_e32 v184, 1.0, v242
	v_add_f32_e32 v185, 1.0, v243
	v_lshlrev_b32_e32 v242, 16, v186
	v_and_b32_e32 v243, 0xffff0000, v186
	v_mul_f32_e32 v186, v122, v237
	v_lshlrev_b32_e32 v188, 16, v190
	v_and_b32_e32 v189, 0xffff0000, v190
	v_mul_f32_e32 v186, 0xbfb8aa3b, v186
	v_mul_f32_e32 v190, v123, v237
	v_exp_f32_e32 v186, v186
	v_mul_f32_e32 v190, 0xbfb8aa3b, v190
	v_rcp_f32_e32 v184, v184
	v_rcp_f32_e32 v185, v185
	v_exp_f32_e32 v190, v190
	v_add_f32_e32 v186, 1.0, v186
	v_lshlrev_b64 v[216:217], 12, v[208:209]
	v_pk_fma_f32 v[184:185], v[184:185], v[242:243], v[188:189]
	v_rcp_f32_e32 v188, v186
	v_add_f32_e32 v186, 1.0, v190
	v_rcp_f32_e32 v189, v186
	v_lshlrev_b32_e32 v190, 16, v191
	v_and_b32_e32 v191, 0xffff0000, v191
	v_lshlrev_b32_e32 v186, 16, v187
	v_and_b32_e32 v187, 0xffff0000, v187
	v_pk_fma_f32 v[186:187], v[188:189], v[186:187], v[190:191]
	v_mul_f32_e32 v188, v108, v237
	v_mul_f32_e32 v189, v109, v237
	v_mul_f32_e32 v188, 0xbfb8aa3b, v188
	v_mul_f32_e32 v189, 0xbfb8aa3b, v189
	v_exp_f32_e32 v188, v188
	v_exp_f32_e32 v189, v189
	v_lshl_add_u64 v[216:217], s[60:61], 0, v[216:217]
	v_lshlrev_b64 v[210:211], 2, v[210:211]
	v_lshl_add_u64 v[216:217], v[216:217], 0, v[210:211]
	global_store_dwordx4 v[216:217], v[184:187], off offset:16 nt
	global_store_dwordx4 v[216:217], v[238:241], off nt
	s_mov_b64 s[16:17], -1
	v_add_f32_e32 v184, 1.0, v188
	v_add_f32_e32 v185, 1.0, v189
	v_lshlrev_b32_e32 v188, 16, v176
	v_and_b32_e32 v189, 0xffff0000, v176
	v_mul_f32_e32 v176, v110, v237
	s_waitcnt vmcnt(14)
	v_lshlrev_b32_e32 v186, 16, v180
	v_and_b32_e32 v187, 0xffff0000, v180
	v_mul_f32_e32 v176, 0xbfb8aa3b, v176
	v_mul_f32_e32 v180, v111, v237
	v_rcp_f32_e32 v184, v184
	v_rcp_f32_e32 v185, v185
	v_exp_f32_e32 v176, v176
	v_mul_f32_e32 v180, 0xbfb8aa3b, v180
	v_exp_f32_e32 v180, v180
	v_pk_fma_f32 v[184:185], v[184:185], v[188:189], v[186:187]
	v_add_f32_e32 v176, 1.0, v176
	v_mul_f32_e32 v188, v104, v237
	v_mul_f32_e32 v189, v105, v237
	v_rcp_f32_e32 v186, v176
	v_add_f32_e32 v176, 1.0, v180
	v_mul_f32_e32 v188, 0xbfb8aa3b, v188
	v_mul_f32_e32 v189, 0xbfb8aa3b, v189
	v_rcp_f32_e32 v187, v176
	v_exp_f32_e32 v188, v188
	v_exp_f32_e32 v189, v189
	v_lshlrev_b32_e32 v180, 16, v181
	v_and_b32_e32 v181, 0xffff0000, v181
	v_lshlrev_b32_e32 v176, 16, v177
	v_and_b32_e32 v177, 0xffff0000, v177
	v_pk_fma_f32 v[186:187], v[186:187], v[176:177], v[180:181]
	v_add_f32_e32 v176, 1.0, v188
	v_add_f32_e32 v177, 1.0, v189
	v_lshlrev_b32_e32 v188, 16, v178
	v_and_b32_e32 v189, 0xffff0000, v178
	v_mul_f32_e32 v178, v106, v237
	v_lshlrev_b32_e32 v180, 16, v182
	v_and_b32_e32 v181, 0xffff0000, v182
	v_mul_f32_e32 v178, 0xbfb8aa3b, v178
	v_mul_f32_e32 v182, v107, v237
	v_exp_f32_e32 v178, v178
	v_mul_f32_e32 v182, 0xbfb8aa3b, v182
	v_rcp_f32_e32 v176, v176
	v_rcp_f32_e32 v177, v177
	v_exp_f32_e32 v182, v182
	v_add_f32_e32 v178, 1.0, v178
	s_and_b64 vcc, exec, s[48:49]
	v_pk_fma_f32 v[176:177], v[176:177], v[188:189], v[180:181]
	v_rcp_f32_e32 v180, v178
	v_add_f32_e32 v178, 1.0, v182
	v_rcp_f32_e32 v181, v178
	v_lshlrev_b32_e32 v182, 16, v183
	v_and_b32_e32 v183, 0xffff0000, v183
	v_lshlrev_b32_e32 v178, 16, v179
	v_and_b32_e32 v179, 0xffff0000, v179
	v_pk_fma_f32 v[178:179], v[180:181], v[178:179], v[182:183]
	global_store_dwordx4 v[216:217], v[184:187], off offset:128 nt
	global_store_dwordx4 v[216:217], v[176:179], off offset:144 nt
	s_waitcnt vmcnt(15)
	v_lshlrev_b32_e32 v182, 16, v168
	v_and_b32_e32 v183, 0xffff0000, v168
	v_mul_f32_e32 v178, v116, v236
	v_mul_f32_e32 v179, v117, v236
	v_mul_f32_e32 v178, 0xbfb8aa3b, v178
	v_mul_f32_e32 v179, 0xbfb8aa3b, v179
	v_add_u32_e32 v176, s20, v222
	v_exp_f32_e32 v178, v178
	v_exp_f32_e32 v179, v179
	v_ashrrev_i32_e32 v177, 31, v176
	v_lshlrev_b64 v[176:177], 12, v[176:177]
	v_lshl_add_u64 v[176:177], s[60:61], 0, v[176:177]
	v_mul_f32_e32 v168, v118, v236
	v_lshl_add_u64 v[180:181], v[176:177], 0, v[210:211]
	v_add_f32_e32 v176, 1.0, v178
	v_add_f32_e32 v177, 1.0, v179
	s_waitcnt vmcnt(13)
; __device__ __forceinline__ float bf_lo(unsigned w) { return __uint_as_float(w << 16); }
; __device__ __forceinline__ float bf_hi(unsigned w) { return __uint_as_float(w & 0xffff0000u); }
; __device__ __forceinline__ float sigmoidf_(float x) { return fast_rcp(1.f + fast_exp2(-LOG2E * x)); }
;     __device__ __forceinline__ void operator()(f32x4 (&acc)[2][2][4][2], const Unit& u, int wr, int wc, int fr, int fq) const {
;     ...
;                     y0[0] = bf_lo(hh[0]) + sigmoidf_(rstd[m] * a0[0]) * bf_lo(p[0]); y0[1] = bf_hi(hh[0]) + sigmoidf_(rstd[m] * a0[1]) * bf_hi(p[0]);
;                     y0[2] = bf_lo(hh[1]) + sigmoidf_(rstd[m] * a0[2]) * bf_lo(p[1]); y0[3] = bf_hi(hh[1]) + sigmoidf_(rstd[m] * a0[3]) * bf_hi(p[1]);
;                     y1[0] = bf_lo(hh[2]) + sigmoidf_(rstd[m] * a1[0]) * bf_lo(p[2]); y1[1] = bf_hi(hh[2]) + sigmoidf_(rstd[m] * a1[1]) * bf_hi(p[2]);
;                     y1[2] = bf_lo(hh[3]) + sigmoidf_(rstd[m] * a1[2]) * bf_lo(p[3]); y1[3] = bf_hi(hh[3]) + sigmoidf_(rstd[m] * a1[3]) * bf_hi(p[3]);
;                     __builtin_nontemporal_store(y0, (f32x4*)(orow + 32 * bj)); __builtin_nontemporal_store(y1, (f32x4*)(orow + 32 * bj + 4));
	v_lshlrev_b32_e32 v178, 16, v172
	v_and_b32_e32 v179, 0xffff0000, v172
	v_mul_f32_e32 v168, 0xbfb8aa3b, v168
	v_mul_f32_e32 v172, v119, v236
	v_rcp_f32_e32 v176, v176
	v_rcp_f32_e32 v177, v177
	v_exp_f32_e32 v168, v168
	v_mul_f32_e32 v172, 0xbfb8aa3b, v172
	v_exp_f32_e32 v172, v172
	v_pk_fma_f32 v[176:177], v[176:177], v[182:183], v[178:179]
	v_add_f32_e32 v168, 1.0, v168
	v_mul_f32_e32 v182, v112, v236
	v_mul_f32_e32 v183, v113, v236
	v_rcp_f32_e32 v178, v168
	v_add_f32_e32 v168, 1.0, v172
	v_mul_f32_e32 v182, 0xbfb8aa3b, v182
	v_mul_f32_e32 v183, 0xbfb8aa3b, v183
	v_rcp_f32_e32 v179, v168
	v_exp_f32_e32 v182, v182
	v_exp_f32_e32 v183, v183
	v_lshlrev_b32_e32 v172, 16, v173
	v_and_b32_e32 v173, 0xffff0000, v173
	v_lshlrev_b32_e32 v168, 16, v169
	v_and_b32_e32 v169, 0xffff0000, v169
	v_pk_fma_f32 v[178:179], v[178:179], v[168:169], v[172:173]
	v_add_f32_e32 v168, 1.0, v182
	v_add_f32_e32 v169, 1.0, v183
	v_lshlrev_b32_e32 v182, 16, v170
	v_and_b32_e32 v183, 0xffff0000, v170
	v_mul_f32_e32 v170, v114, v236
	v_lshlrev_b32_e32 v172, 16, v174
	v_and_b32_e32 v173, 0xffff0000, v174
	v_mul_f32_e32 v170, 0xbfb8aa3b, v170
	v_mul_f32_e32 v174, v115, v236
	v_exp_f32_e32 v170, v170
	v_mul_f32_e32 v174, 0xbfb8aa3b, v174
	v_rcp_f32_e32 v168, v168
	v_rcp_f32_e32 v169, v169
	v_exp_f32_e32 v174, v174
	v_add_f32_e32 v170, 1.0, v170
	global_store_dwordx4 v[180:181], v[176:179], off nt
	v_pk_fma_f32 v[168:169], v[168:169], v[182:183], v[172:173]
	v_rcp_f32_e32 v172, v170
	v_add_f32_e32 v170, 1.0, v174
	v_rcp_f32_e32 v173, v170
	v_lshlrev_b32_e32 v174, 16, v175
	v_and_b32_e32 v175, 0xffff0000, v175
	v_lshlrev_b32_e32 v170, 16, v171
	v_and_b32_e32 v171, 0xffff0000, v171
	v_pk_fma_f32 v[170:171], v[172:173], v[170:171], v[174:175]
	v_mul_f32_e32 v172, v92, v236
	v_mul_f32_e32 v173, v93, v236
	v_mul_f32_e32 v172, 0xbfb8aa3b, v172
	v_mul_f32_e32 v173, 0xbfb8aa3b, v173
	v_exp_f32_e32 v172, v172
	v_exp_f32_e32 v173, v173
	global_store_dwordx4 v[180:181], v[168:171], off offset:16 nt
	v_add_u32_e32 v216, s20, v225
	v_ashrrev_i32_e32 v217, 31, v216
	v_add_f32_e32 v168, 1.0, v172
	v_add_f32_e32 v169, 1.0, v173
	v_lshlrev_b32_e32 v172, 16, v160
	v_and_b32_e32 v173, 0xffff0000, v160
	v_mul_f32_e32 v160, v94, v236
	s_waitcnt vmcnt(14)
	v_lshlrev_b32_e32 v170, 16, v164
	v_and_b32_e32 v171, 0xffff0000, v164
	v_mul_f32_e32 v160, 0xbfb8aa3b, v160
	v_mul_f32_e32 v164, v95, v236
	v_rcp_f32_e32 v168, v168
	v_rcp_f32_e32 v169, v169
	v_exp_f32_e32 v160, v160
	v_mul_f32_e32 v164, 0xbfb8aa3b, v164
	v_exp_f32_e32 v164, v164
	v_pk_fma_f32 v[168:169], v[168:169], v[172:173], v[170:171]
	v_add_f32_e32 v160, 1.0, v160
	v_mul_f32_e32 v172, v88, v236
	v_mul_f32_e32 v173, v89, v236
	v_rcp_f32_e32 v170, v160
	v_add_f32_e32 v160, 1.0, v164
	v_mul_f32_e32 v172, 0xbfb8aa3b, v172
	v_mul_f32_e32 v173, 0xbfb8aa3b, v173
	v_rcp_f32_e32 v171, v160
	v_exp_f32_e32 v172, v172
	v_exp_f32_e32 v173, v173
	v_lshlrev_b32_e32 v164, 16, v165
	v_and_b32_e32 v165, 0xffff0000, v165
	v_lshlrev_b32_e32 v160, 16, v161
	v_and_b32_e32 v161, 0xffff0000, v161
	v_pk_fma_f32 v[170:171], v[170:171], v[160:161], v[164:165]
	v_add_f32_e32 v160, 1.0, v172
	v_add_f32_e32 v161, 1.0, v173
	v_lshlrev_b32_e32 v172, 16, v162
	v_and_b32_e32 v173, 0xffff0000, v162
	v_mul_f32_e32 v162, v90, v236
	v_lshlrev_b32_e32 v164, 16, v166
	v_and_b32_e32 v165, 0xffff0000, v166
	v_mul_f32_e32 v162, 0xbfb8aa3b, v162
	v_mul_f32_e32 v166, v91, v236
	v_exp_f32_e32 v162, v162
	v_mul_f32_e32 v166, 0xbfb8aa3b, v166
	v_rcp_f32_e32 v160, v160
	v_rcp_f32_e32 v161, v161
	v_exp_f32_e32 v166, v166
	v_add_f32_e32 v162, 1.0, v162
	v_pk_fma_f32 v[160:161], v[160:161], v[172:173], v[164:165]
	v_rcp_f32_e32 v164, v162
	v_add_f32_e32 v162, 1.0, v166
	v_rcp_f32_e32 v165, v162
	v_lshlrev_b32_e32 v166, 16, v167
	v_and_b32_e32 v167, 0xffff0000, v167
	v_lshlrev_b32_e32 v162, 16, v163
	v_and_b32_e32 v163, 0xffff0000, v163
	v_pk_fma_f32 v[162:163], v[164:165], v[162:163], v[166:167]
	global_store_dwordx4 v[180:181], v[168:171], off offset:128 nt
	global_store_dwordx4 v[180:181], v[160:163], off offset:144 nt
	s_waitcnt vmcnt(15)
	v_lshlrev_b32_e32 v166, 16, v152
	v_and_b32_e32 v167, 0xffff0000, v152
	v_mul_f32_e32 v162, v100, v219
	v_mul_f32_e32 v163, v101, v219
	v_mul_f32_e32 v162, 0xbfb8aa3b, v162
	v_mul_f32_e32 v163, 0xbfb8aa3b, v163
	v_add_u32_e32 v160, s20, v223
	v_exp_f32_e32 v162, v162
	v_exp_f32_e32 v163, v163
	v_ashrrev_i32_e32 v161, 31, v160
	v_lshlrev_b64 v[160:161], 12, v[160:161]
	v_lshl_add_u64 v[160:161], s[60:61], 0, v[160:161]
	v_mul_f32_e32 v152, v102, v219
	v_lshl_add_u64 v[164:165], v[160:161], 0, v[210:211]
	v_add_f32_e32 v160, 1.0, v162
	v_add_f32_e32 v161, 1.0, v163
	s_waitcnt vmcnt(13)
; __device__ __forceinline__ float bf_lo(unsigned w) { return __uint_as_float(w << 16); }
; __device__ __forceinline__ float bf_hi(unsigned w) { return __uint_as_float(w & 0xffff0000u); }
; __device__ __forceinline__ float sigmoidf_(float x) { return fast_rcp(1.f + fast_exp2(-LOG2E * x)); }
;     __device__ __forceinline__ void operator()(f32x4 (&acc)[2][2][4][2], const Unit& u, int wr, int wc, int fr, int fq) const {
;     ...
;                     y0[0] = bf_lo(hh[0]) + sigmoidf_(rstd[m] * a0[0]) * bf_lo(p[0]); y0[1] = bf_hi(hh[0]) + sigmoidf_(rstd[m] * a0[1]) * bf_hi(p[0]);
;                     y0[2] = bf_lo(hh[1]) + sigmoidf_(rstd[m] * a0[2]) * bf_lo(p[1]); y0[3] = bf_hi(hh[1]) + sigmoidf_(rstd[m] * a0[3]) * bf_hi(p[1]);
;                     y1[0] = bf_lo(hh[2]) + sigmoidf_(rstd[m] * a1[0]) * bf_lo(p[2]); y1[1] = bf_hi(hh[2]) + sigmoidf_(rstd[m] * a1[1]) * bf_hi(p[2]);
;                     y1[2] = bf_lo(hh[3]) + sigmoidf_(rstd[m] * a1[2]) * bf_lo(p[3]); y1[3] = bf_hi(hh[3]) + sigmoidf_(rstd[m] * a1[3]) * bf_hi(p[3]);
;                     __builtin_nontemporal_store(y0, (f32x4*)(orow + 32 * bj)); __builtin_nontemporal_store(y1, (f32x4*)(orow + 32 * bj + 4));
	v_lshlrev_b32_e32 v162, 16, v156
	v_and_b32_e32 v163, 0xffff0000, v156
	v_mul_f32_e32 v152, 0xbfb8aa3b, v152
	v_mul_f32_e32 v156, v103, v219
	v_rcp_f32_e32 v160, v160
	v_rcp_f32_e32 v161, v161
	v_exp_f32_e32 v152, v152
	v_mul_f32_e32 v156, 0xbfb8aa3b, v156
	v_exp_f32_e32 v156, v156
	v_pk_fma_f32 v[160:161], v[160:161], v[166:167], v[162:163]
	v_add_f32_e32 v152, 1.0, v152
	v_mul_f32_e32 v166, v96, v219
	v_mul_f32_e32 v167, v97, v219
	v_rcp_f32_e32 v162, v152
	v_add_f32_e32 v152, 1.0, v156
	v_mul_f32_e32 v166, 0xbfb8aa3b, v166
	v_mul_f32_e32 v167, 0xbfb8aa3b, v167
	v_rcp_f32_e32 v163, v152
	v_exp_f32_e32 v166, v166
	v_exp_f32_e32 v167, v167
	v_lshlrev_b32_e32 v156, 16, v157
	v_and_b32_e32 v157, 0xffff0000, v157
	v_lshlrev_b32_e32 v152, 16, v153
	v_and_b32_e32 v153, 0xffff0000, v153
	v_pk_fma_f32 v[162:163], v[162:163], v[152:153], v[156:157]
	v_add_f32_e32 v152, 1.0, v166
	v_add_f32_e32 v153, 1.0, v167
	v_lshlrev_b32_e32 v166, 16, v154
	v_and_b32_e32 v167, 0xffff0000, v154
	v_mul_f32_e32 v154, v98, v219
	v_lshlrev_b32_e32 v156, 16, v158
	v_and_b32_e32 v157, 0xffff0000, v158
	v_mul_f32_e32 v154, 0xbfb8aa3b, v154
	v_mul_f32_e32 v158, v99, v219
	v_exp_f32_e32 v154, v154
	v_mul_f32_e32 v158, 0xbfb8aa3b, v158
	v_rcp_f32_e32 v152, v152
	v_rcp_f32_e32 v153, v153
	v_exp_f32_e32 v158, v158
	v_add_f32_e32 v154, 1.0, v154
	global_store_dwordx4 v[164:165], v[160:163], off nt
	v_pk_fma_f32 v[152:153], v[152:153], v[166:167], v[156:157]
	v_rcp_f32_e32 v156, v154
	v_add_f32_e32 v154, 1.0, v158
	v_rcp_f32_e32 v157, v154
	v_lshlrev_b32_e32 v158, 16, v159
	v_and_b32_e32 v159, 0xffff0000, v159
	v_lshlrev_b32_e32 v154, 16, v155
	v_and_b32_e32 v155, 0xffff0000, v155
	v_pk_fma_f32 v[154:155], v[156:157], v[154:155], v[158:159]
	v_mul_f32_e32 v156, v76, v219
	v_mul_f32_e32 v157, v77, v219
	v_mul_f32_e32 v156, 0xbfb8aa3b, v156
	v_mul_f32_e32 v157, 0xbfb8aa3b, v157
	v_exp_f32_e32 v156, v156
	v_exp_f32_e32 v157, v157
	global_store_dwordx4 v[164:165], v[152:155], off offset:16 nt
	s_nop 1
	v_add_f32_e32 v152, 1.0, v156
	v_add_f32_e32 v153, 1.0, v157
	v_lshlrev_b32_e32 v156, 16, v144
	v_and_b32_e32 v157, 0xffff0000, v144
	v_mul_f32_e32 v144, v78, v219
	s_waitcnt vmcnt(14)
	v_lshlrev_b32_e32 v154, 16, v148
	v_and_b32_e32 v155, 0xffff0000, v148
	v_mul_f32_e32 v144, 0xbfb8aa3b, v144
	v_mul_f32_e32 v148, v79, v219
	v_rcp_f32_e32 v152, v152
	v_rcp_f32_e32 v153, v153
	v_exp_f32_e32 v144, v144
	v_mul_f32_e32 v148, 0xbfb8aa3b, v148
	v_exp_f32_e32 v148, v148
	v_pk_fma_f32 v[152:153], v[152:153], v[156:157], v[154:155]
	v_add_f32_e32 v144, 1.0, v144
	v_mul_f32_e32 v156, v72, v219
	v_mul_f32_e32 v157, v73, v219
	v_rcp_f32_e32 v154, v144
	v_add_f32_e32 v144, 1.0, v148
	v_mul_f32_e32 v156, 0xbfb8aa3b, v156
	v_mul_f32_e32 v157, 0xbfb8aa3b, v157
	v_rcp_f32_e32 v155, v144
	v_exp_f32_e32 v156, v156
	v_exp_f32_e32 v157, v157
	v_lshlrev_b32_e32 v148, 16, v149
	v_and_b32_e32 v149, 0xffff0000, v149
	v_lshlrev_b32_e32 v144, 16, v145
	v_and_b32_e32 v145, 0xffff0000, v145
	v_pk_fma_f32 v[154:155], v[154:155], v[144:145], v[148:149]
	v_add_f32_e32 v144, 1.0, v156
	v_add_f32_e32 v145, 1.0, v157
	v_lshlrev_b32_e32 v156, 16, v146
	v_and_b32_e32 v157, 0xffff0000, v146
	v_mul_f32_e32 v146, v74, v219
	v_lshlrev_b32_e32 v148, 16, v150
	v_and_b32_e32 v149, 0xffff0000, v150
	v_mul_f32_e32 v146, 0xbfb8aa3b, v146
	v_mul_f32_e32 v150, v75, v219
	v_exp_f32_e32 v146, v146
	v_mul_f32_e32 v150, 0xbfb8aa3b, v150
	v_rcp_f32_e32 v144, v144
	v_rcp_f32_e32 v145, v145
	v_exp_f32_e32 v150, v150
	v_add_f32_e32 v146, 1.0, v146
	v_pk_fma_f32 v[144:145], v[144:145], v[156:157], v[148:149]
	v_rcp_f32_e32 v148, v146
	v_add_f32_e32 v146, 1.0, v150
	v_rcp_f32_e32 v149, v146
	v_lshlrev_b32_e32 v150, 16, v151
	v_and_b32_e32 v151, 0xffff0000, v151
	v_lshlrev_b32_e32 v146, 16, v147
	v_and_b32_e32 v147, 0xffff0000, v147
	v_pk_fma_f32 v[146:147], v[148:149], v[146:147], v[150:151]
	global_store_dwordx4 v[164:165], v[152:155], off offset:128 nt
	global_store_dwordx4 v[164:165], v[144:147], off offset:144 nt
	s_waitcnt vmcnt(15)
	v_lshlrev_b32_e32 v150, 16, v136
	v_and_b32_e32 v151, 0xffff0000, v136
	v_mul_f32_e32 v146, v84, v218
	v_mul_f32_e32 v147, v85, v218
	v_mul_f32_e32 v146, 0xbfb8aa3b, v146
	v_mul_f32_e32 v147, 0xbfb8aa3b, v147
	v_add_u32_e32 v144, s20, v224
	v_exp_f32_e32 v146, v146
	v_exp_f32_e32 v147, v147
	v_ashrrev_i32_e32 v145, 31, v144
	v_lshlrev_b64 v[144:145], 12, v[144:145]
	v_lshl_add_u64 v[144:145], s[60:61], 0, v[144:145]
	v_mul_f32_e32 v136, v86, v218
	v_lshl_add_u64 v[148:149], v[144:145], 0, v[210:211]
	v_add_f32_e32 v144, 1.0, v146
	v_add_f32_e32 v145, 1.0, v147
	s_waitcnt vmcnt(13)
; __device__ __forceinline__ float bf_lo(unsigned w) { return __uint_as_float(w << 16); }
; __device__ __forceinline__ float bf_hi(unsigned w) { return __uint_as_float(w & 0xffff0000u); }
; __device__ __forceinline__ float sigmoidf_(float x) { return fast_rcp(1.f + fast_exp2(-LOG2E * x)); }
;     __device__ __forceinline__ void operator()(f32x4 (&acc)[2][2][4][2], const Unit& u, int wr, int wc, int fr, int fq) const {
;     ...
;             for (int m = 0; m < 4; ++m) { const int r = EPI_ROWS(ai, m);
; #pragma unroll
;                 for (int bj = 0; bj < 2; ++bj) { pw[m][bj] = *(const u32x4*)(PLE + (size_t)r * DM + c0 + 32 * bj); hw[m][bj] = *(const u32x4*)(HP + (size_t)r * LDHP + c0 + 32 * bj); }
;                 if (rs) rstd[m] = rs[u.ti * 256 + ai * HALF + wr * 64 + m * 16 + fr];
;                 else { const f32x4* sp = (const f32x4*)(SS + (size_t)r * 16); const f32x4 s0 = sp[0], s1 = sp[1], s2 = sp[2], s3 = sp[3];
;                     const float st = ((s0[0] + s0[1]) + (s0[2] + s0[3])) + ((s1[0] + s1[1]) + (s1[2] + s1[3])) + ((s2[0] + s2[1]) + (s2[2] + s2[3])) + ((s3[0] + s3[1]) + (s3[2] + s3[3]));
;                     rstd[m] = rsqrtf(st * (1.f / DM) + EPS); } }
;             asm volatile("" ::: "memory");
; #pragma unroll
;             for (int m = 0; m < 4; ++m) {
;                 float* orow = out + (size_t)EPI_ROWS(ai, m) * DM + c0;
; #pragma unroll
;                 for (int bj = 0; bj < 2; ++bj) {
;                     const f32x4 a0 = acc[ai][bj][m][0], a1 = acc[ai][bj][m][1];
;                     const u32x4 p = pw[m][bj], hh = hw[m][bj];
;                     f32x4 y0, y1;
;                     y0[0] = bf_lo(hh[0]) + sigmoidf_(rstd[m] * a0[0]) * bf_lo(p[0]); y0[1] = bf_hi(hh[0]) + sigmoidf_(rstd[m] * a0[1]) * bf_hi(p[0]);
;                     y0[2] = bf_lo(hh[1]) + sigmoidf_(rstd[m] * a0[2]) * bf_lo(p[1]); y0[3] = bf_hi(hh[1]) + sigmoidf_(rstd[m] * a0[3]) * bf_hi(p[1]);
;                     y1[0] = bf_lo(hh[2]) + sigmoidf_(rstd[m] * a1[0]) * bf_lo(p[2]); y1[1] = bf_hi(hh[2]) + sigmoidf_(rstd[m] * a1[1]) * bf_hi(p[2]);
;                     y1[2] = bf_lo(hh[3]) + sigmoidf_(rstd[m] * a1[2]) * bf_lo(p[3]); y1[3] = bf_hi(hh[3]) + sigmoidf_(rstd[m] * a1[3]) * bf_hi(p[3]);
;                     __builtin_nontemporal_store(y0, (f32x4*)(orow + 32 * bj)); __builtin_nontemporal_store(y1, (f32x4*)(orow + 32 * bj + 4));
	v_lshlrev_b32_e32 v146, 16, v140
	v_and_b32_e32 v147, 0xffff0000, v140
	v_mul_f32_e32 v136, 0xbfb8aa3b, v136
	v_mul_f32_e32 v140, v87, v218
	v_rcp_f32_e32 v144, v144
	v_rcp_f32_e32 v145, v145
	v_exp_f32_e32 v136, v136
	v_mul_f32_e32 v140, 0xbfb8aa3b, v140
	v_exp_f32_e32 v140, v140
	v_pk_fma_f32 v[144:145], v[144:145], v[150:151], v[146:147]
	v_add_f32_e32 v136, 1.0, v136
	v_mul_f32_e32 v150, v80, v218
	v_mul_f32_e32 v151, v81, v218
	v_rcp_f32_e32 v146, v136
	v_add_f32_e32 v136, 1.0, v140
	v_mul_f32_e32 v150, 0xbfb8aa3b, v150
	v_mul_f32_e32 v151, 0xbfb8aa3b, v151
	v_rcp_f32_e32 v147, v136
	v_exp_f32_e32 v150, v150
	v_exp_f32_e32 v151, v151
	v_lshlrev_b32_e32 v140, 16, v141
	v_and_b32_e32 v141, 0xffff0000, v141
	v_lshlrev_b32_e32 v136, 16, v137
	v_and_b32_e32 v137, 0xffff0000, v137
	v_pk_fma_f32 v[146:147], v[146:147], v[136:137], v[140:141]
	v_add_f32_e32 v136, 1.0, v150
	v_add_f32_e32 v137, 1.0, v151
	v_lshlrev_b32_e32 v150, 16, v138
	v_and_b32_e32 v151, 0xffff0000, v138
	v_mul_f32_e32 v138, v82, v218
	v_lshlrev_b32_e32 v140, 16, v142
	v_and_b32_e32 v141, 0xffff0000, v142
	v_mul_f32_e32 v138, 0xbfb8aa3b, v138
	v_mul_f32_e32 v142, v83, v218
	v_exp_f32_e32 v138, v138
	v_mul_f32_e32 v142, 0xbfb8aa3b, v142
	v_rcp_f32_e32 v136, v136
	v_rcp_f32_e32 v137, v137
	v_exp_f32_e32 v142, v142
	v_add_f32_e32 v138, 1.0, v138
	global_store_dwordx4 v[148:149], v[144:147], off nt
	v_pk_fma_f32 v[136:137], v[136:137], v[150:151], v[140:141]
	v_rcp_f32_e32 v140, v138
	v_add_f32_e32 v138, 1.0, v142
	v_rcp_f32_e32 v141, v138
	v_lshlrev_b32_e32 v142, 16, v143
	v_and_b32_e32 v143, 0xffff0000, v143
	v_lshlrev_b32_e32 v138, 16, v139
	v_and_b32_e32 v139, 0xffff0000, v139
	v_pk_fma_f32 v[138:139], v[140:141], v[138:139], v[142:143]
	v_mul_f32_e32 v140, v68, v218
	v_mul_f32_e32 v141, v69, v218
	v_mul_f32_e32 v140, 0xbfb8aa3b, v140
	v_mul_f32_e32 v141, 0xbfb8aa3b, v141
	v_exp_f32_e32 v140, v140
	v_exp_f32_e32 v141, v141
	global_store_dwordx4 v[148:149], v[136:139], off offset:16 nt
	s_nop 1
	v_add_f32_e32 v136, 1.0, v140
	v_add_f32_e32 v137, 1.0, v141
	v_lshlrev_b32_e32 v140, 16, v128
	v_and_b32_e32 v141, 0xffff0000, v128
	v_mul_f32_e32 v128, v70, v218
	s_waitcnt vmcnt(14)
	v_lshlrev_b32_e32 v138, 16, v132
	v_and_b32_e32 v139, 0xffff0000, v132
	v_mul_f32_e32 v128, 0xbfb8aa3b, v128
	v_mul_f32_e32 v132, v71, v218
	v_rcp_f32_e32 v136, v136
	v_rcp_f32_e32 v137, v137
	v_exp_f32_e32 v128, v128
	v_mul_f32_e32 v132, 0xbfb8aa3b, v132
	v_exp_f32_e32 v132, v132
	v_pk_fma_f32 v[136:137], v[136:137], v[140:141], v[138:139]
	v_add_f32_e32 v128, 1.0, v128
	v_mul_f32_e32 v140, v64, v218
	v_mul_f32_e32 v141, v65, v218
	v_rcp_f32_e32 v138, v128
	v_add_f32_e32 v128, 1.0, v132
	v_mul_f32_e32 v140, 0xbfb8aa3b, v140
	v_mul_f32_e32 v141, 0xbfb8aa3b, v141
	v_rcp_f32_e32 v139, v128
	v_exp_f32_e32 v140, v140
	v_exp_f32_e32 v141, v141
	v_lshlrev_b32_e32 v132, 16, v133
	v_and_b32_e32 v133, 0xffff0000, v133
	v_lshlrev_b32_e32 v128, 16, v129
	v_and_b32_e32 v129, 0xffff0000, v129
	v_pk_fma_f32 v[138:139], v[138:139], v[128:129], v[132:133]
	v_add_f32_e32 v128, 1.0, v140
	v_add_f32_e32 v129, 1.0, v141
	v_lshlrev_b32_e32 v140, 16, v130
	v_and_b32_e32 v141, 0xffff0000, v130
	v_mul_f32_e32 v130, v66, v218
	v_lshlrev_b32_e32 v132, 16, v134
	v_and_b32_e32 v133, 0xffff0000, v134
	v_mul_f32_e32 v130, 0xbfb8aa3b, v130
	v_mul_f32_e32 v134, v67, v218
	v_exp_f32_e32 v130, v130
	v_mul_f32_e32 v134, 0xbfb8aa3b, v134
	v_rcp_f32_e32 v128, v128
	v_rcp_f32_e32 v129, v129
	v_exp_f32_e32 v134, v134
	v_add_f32_e32 v130, 1.0, v130
	v_pk_fma_f32 v[128:129], v[128:129], v[140:141], v[132:133]
	v_rcp_f32_e32 v132, v130
	v_add_f32_e32 v130, 1.0, v134
	v_rcp_f32_e32 v133, v130
	v_lshlrev_b32_e32 v134, 16, v135
	v_and_b32_e32 v135, 0xffff0000, v135
	v_lshlrev_b32_e32 v130, 16, v131
	v_and_b32_e32 v131, 0xffff0000, v131
	v_pk_fma_f32 v[130:131], v[132:133], v[130:131], v[134:135]
	global_store_dwordx4 v[148:149], v[136:139], off offset:128 nt
	global_store_dwordx4 v[148:149], v[128:131], off offset:144 nt
	s_nop 1
	v_lshlrev_b64 v[128:129], 11, v[216:217]
	v_lshl_add_u64 v[128:129], v[212:213], 0, v[128:129]
	v_mad_i64_i32 v[130:131], s[2:3], v216, s39, v[214:215]
	global_load_dwordx4 v[184:187], v[128:129], off
	global_load_dwordx4 v[176:179], v[128:129], off offset:64
	global_load_dwordx4 v[188:191], v[130:131], off
	global_load_dwordx4 v[180:183], v[130:131], off offset:64
	s_cbranch_vccz .LBB0_1014
	v_lshlrev_b64 v[128:129], 6, v[216:217]
	v_lshl_add_u64 v[140:141], s[8:9], 0, v[128:129]
	global_load_dwordx4 v[128:131], v[140:141], off
	global_load_dwordx4 v[132:135], v[140:141], off offset:16
	global_load_dwordx4 v[136:139], v[140:141], off offset:32
	s_nop 0
	global_load_dwordx4 v[140:143], v[140:141], off offset:48
	s_mov_b64 s[16:17], 0
	s_waitcnt vmcnt(3)
	v_mov_b32_e32 v144, v129
	v_mov_b32_e32 v145, v130
	v_mov_b32_e32 v129, v131
	s_waitcnt vmcnt(2)
	v_mov_b32_e32 v130, v133
	v_mov_b32_e32 v131, v134
	v_mov_b32_e32 v133, v135
	v_pk_add_f32 v[128:129], v[144:145], v[128:129]
	v_pk_add_f32 v[130:131], v[130:131], v[132:133]
	v_pk_add_f32 v[128:129], v[128:129], v[128:129] op_sel:[0,1] op_sel_hi:[1,0]
	v_pk_add_f32 v[130:131], v[130:131], v[130:131] op_sel:[0,1] op_sel_hi:[1,0]
	s_waitcnt vmcnt(1)
	v_add_f32_e32 v134, v136, v137
	v_add_f32_e32 v136, v138, v139
	s_waitcnt vmcnt(0)
	v_mov_b32_e32 v135, v142
	v_mov_b32_e32 v137, v143
	v_mov_b32_e32 v129, v140
	v_mov_b32_e32 v131, v141
	v_pk_add_f32 v[132:133], v[134:135], v[136:137]
	v_pk_add_f32 v[128:129], v[128:129], v[130:131]
	s_nop 0
	v_pk_add_f32 v[128:129], v[128:129], v[132:133]
	s_nop 0
	v_add_f32_e32 v128, v128, v129
	v_fmamk_f32 v128, v128, 0x3a800000, v234
	v_mul_f32_e32 v129, 0x4b800000, v128
	v_cmp_gt_f32_e32 vcc, s40, v128
	s_nop 1
	v_cndmask_b32_e32 v128, v128, v129, vcc
	v_rsq_f32_e32 v128, v128
	s_nop 0
	v_mul_f32_e32 v129, 0x45800000, v128
	v_cndmask_b32_e32 v238, v128, v129, vcc
